# loop-edge: K-loop counter/pointer SALU block moved in front of the loop-back barrier (3 loops)
# baseline (speedup 1.0000x reference)
.LBB0_180:
	ds_read_b128 v[152:155], v159
	ds_read_b128 v[162:165], v159 offset:1024
	ds_read_b128 v[166:169], v159 offset:2048
	ds_read_b128 v[170:173], v159 offset:3072
	ds_read_b128 v[174:177], v160
	ds_read_b128 v[178:181], v160 offset:1024
	ds_read_b128 v[182:185], v160 offset:2048
	ds_read_b128 v[186:189], v160 offset:3072
	s_add_u32 s4, s0, 0xfffc0080
	s_addc_u32 s5, s1, -1
	s_cmp_eq_u32 vcc_lo, 12
	s_cselect_b32 s83, s39, s5
	s_cselect_b32 s82, s38, s4
	s_cselect_b32 s5, s73, s79
	s_cselect_b32 s4, s72, s53
	v_lshl_add_u64 v[198:199], s[0:1], 0, v[144:145]
	s_add_i32 m0, s43, 0xc000
	ds_read_b128 v[190:193], v161
	ds_read_b128 v[194:197], v161 offset:1024
	ds_read_b128 v[202:205], v161 offset:2048
	ds_read_b128 v[206:209], v161 offset:3072
	ds_read_b128 v[210:213], v161 offset:4096
	ds_read_b128 v[214:217], v161 offset:5120
	ds_read_b128 v[218:221], v161 offset:6144
	ds_read_b128 v[222:225], v161 offset:7168
	global_load_lds_dwordx4 v[198:199], off
	v_lshl_add_u64 v[198:199], s[0:1], 0, v[146:147]
	s_add_i32 m0, s43, 0xe000
	s_nop 0
	global_load_lds_dwordx4 v[198:199], off
	s_waitcnt vmcnt(8)
	s_waitcnt lgkmcnt(0)
	s_barrier
	s_setprio 1
	s_waitcnt lgkmcnt(0)
	v_mfma_f32_16x16x32_bf16 v[124:127], v[152:155], v[190:193], v[124:127]
	v_mfma_f32_16x16x32_bf16 v[120:123], v[166:169], v[190:193], v[120:123]
	v_mfma_f32_16x16x32_bf16 v[108:111], v[152:155], v[202:205], v[108:111]
	v_mfma_f32_16x16x32_bf16 v[104:107], v[166:169], v[202:205], v[104:107]
	v_mfma_f32_16x16x32_bf16 v[92:95], v[152:155], v[210:213], v[92:95]
	v_mfma_f32_16x16x32_bf16 v[88:91], v[166:169], v[210:213], v[88:91]
	v_mfma_f32_16x16x32_bf16 v[76:79], v[152:155], v[218:221], v[76:79]
	v_mfma_f32_16x16x32_bf16 v[72:75], v[166:169], v[218:221], v[72:75]
	v_mfma_f32_16x16x32_bf16 v[124:127], v[162:165], v[194:197], v[124:127]
	v_mfma_f32_16x16x32_bf16 v[120:123], v[170:173], v[194:197], v[120:123]
	v_mfma_f32_16x16x32_bf16 v[108:111], v[162:165], v[206:209], v[108:111]
	v_mfma_f32_16x16x32_bf16 v[104:107], v[170:173], v[206:209], v[104:107]
	v_mfma_f32_16x16x32_bf16 v[92:95], v[162:165], v[214:217], v[92:95]
	v_mfma_f32_16x16x32_bf16 v[88:91], v[170:173], v[214:217], v[88:91]
	v_mfma_f32_16x16x32_bf16 v[76:79], v[162:165], v[222:225], v[76:79]
	v_mfma_f32_16x16x32_bf16 v[72:75], v[170:173], v[222:225], v[72:75]
	s_setprio 0
	s_setprio 1
	v_mfma_f32_16x16x32_bf16 v[116:119], v[174:177], v[190:193], v[116:119]
	v_mfma_f32_16x16x32_bf16 v[112:115], v[182:185], v[190:193], v[112:115]
	v_mfma_f32_16x16x32_bf16 v[100:103], v[174:177], v[202:205], v[100:103]
	v_mfma_f32_16x16x32_bf16 v[96:99], v[182:185], v[202:205], v[96:99]
	v_mfma_f32_16x16x32_bf16 v[84:87], v[174:177], v[210:213], v[84:87]
	v_mfma_f32_16x16x32_bf16 v[80:83], v[182:185], v[210:213], v[80:83]
	v_mfma_f32_16x16x32_bf16 v[68:71], v[174:177], v[218:221], v[68:71]
	v_mfma_f32_16x16x32_bf16 v[64:67], v[182:185], v[218:221], v[64:67]
	v_mfma_f32_16x16x32_bf16 v[116:119], v[178:181], v[194:197], v[116:119]
	v_mfma_f32_16x16x32_bf16 v[112:115], v[186:189], v[194:197], v[112:115]
	v_mfma_f32_16x16x32_bf16 v[100:103], v[178:181], v[206:209], v[100:103]
	v_mfma_f32_16x16x32_bf16 v[96:99], v[186:189], v[206:209], v[96:99]
	v_mfma_f32_16x16x32_bf16 v[84:87], v[178:181], v[214:217], v[84:87]
	v_mfma_f32_16x16x32_bf16 v[80:83], v[186:189], v[214:217], v[80:83]
	v_mfma_f32_16x16x32_bf16 v[68:71], v[178:181], v[222:225], v[68:71]
	v_mfma_f32_16x16x32_bf16 v[64:67], v[186:189], v[222:225], v[64:67]
	s_setprio 0
	s_barrier
	s_add_i32 s12, s9, s3
	v_lshl_add_u64 v[198:199], s[4:5], 0, v[132:133]
	s_mov_b32 m0, s12
	ds_read_b128 v[190:193], v161 offset:16384
	ds_read_b128 v[194:197], v161 offset:17408
	ds_read_b128 v[202:205], v161 offset:18432
	ds_read_b128 v[206:209], v161 offset:19456
	ds_read_b128 v[210:213], v161 offset:20480
	ds_read_b128 v[214:217], v161 offset:21504
	ds_read_b128 v[218:221], v161 offset:22528
	ds_read_b128 v[222:225], v161 offset:23552
	global_load_lds_dwordx4 v[198:199], off
	s_add_i32 m0, s12, 0x2000
	s_add_u32 s12, s4, 0x40000
	v_lshl_add_u64 v[226:227], s[4:5], 0, v[128:129]
	s_addc_u32 s13, s5, 0
	s_add_i32 vcc_hi, s10, s3
	global_load_lds_dwordx4 v[226:227], off
	v_lshl_add_u64 v[228:229], s[12:13], 0, v[132:133]
	s_mov_b32 m0, vcc_hi
	v_lshl_add_u64 v[230:231], s[82:83], 0, v[130:131]
	global_load_lds_dwordx4 v[228:229], off
	v_lshl_add_u64 v[228:229], s[12:13], 0, v[128:129]
	s_add_i32 m0, vcc_hi, 0x2000
	s_nop 0
	global_load_lds_dwordx4 v[228:229], off
	v_lshl_add_u64 v[228:229], s[82:83], 0, v[134:135]
	s_mov_b32 m0, s43
	s_nop 0
	global_load_lds_dwordx4 v[228:229], off
	s_mov_b32 m0, s75
	s_nop 0
	global_load_lds_dwordx4 v[230:231], off
	s_waitcnt vmcnt(8)
	s_waitcnt lgkmcnt(0)
	s_barrier
	s_setprio 1
	s_waitcnt lgkmcnt(0)
	v_mfma_f32_16x16x32_bf16 v[60:63], v[152:155], v[190:193], v[60:63]
	v_mfma_f32_16x16x32_bf16 v[56:59], v[166:169], v[190:193], v[56:59]
	v_mfma_f32_16x16x32_bf16 v[44:47], v[152:155], v[202:205], v[44:47]
	v_mfma_f32_16x16x32_bf16 v[40:43], v[166:169], v[202:205], v[40:43]
	v_mfma_f32_16x16x32_bf16 v[28:31], v[152:155], v[210:213], v[28:31]
	v_mfma_f32_16x16x32_bf16 v[24:27], v[166:169], v[210:213], v[24:27]
	v_mfma_f32_16x16x32_bf16 v[12:15], v[152:155], v[218:221], v[12:15]
	v_mfma_f32_16x16x32_bf16 v[8:11], v[166:169], v[218:221], v[8:11]
	v_mfma_f32_16x16x32_bf16 v[60:63], v[162:165], v[194:197], v[60:63]
	v_mfma_f32_16x16x32_bf16 v[56:59], v[170:173], v[194:197], v[56:59]
	v_mfma_f32_16x16x32_bf16 v[44:47], v[162:165], v[206:209], v[44:47]
	v_mfma_f32_16x16x32_bf16 v[40:43], v[170:173], v[206:209], v[40:43]
	v_mfma_f32_16x16x32_bf16 v[28:31], v[162:165], v[214:217], v[28:31]
	v_mfma_f32_16x16x32_bf16 v[24:27], v[170:173], v[214:217], v[24:27]
	v_mfma_f32_16x16x32_bf16 v[12:15], v[162:165], v[222:225], v[12:15]
	v_mfma_f32_16x16x32_bf16 v[8:11], v[170:173], v[222:225], v[8:11]
	s_setprio 0
	s_setprio 1
	v_mfma_f32_16x16x32_bf16 v[52:55], v[174:177], v[190:193], v[52:55]
	v_mfma_f32_16x16x32_bf16 v[48:51], v[182:185], v[190:193], v[48:51]
	v_mfma_f32_16x16x32_bf16 v[36:39], v[174:177], v[202:205], v[36:39]
	v_mfma_f32_16x16x32_bf16 v[32:35], v[182:185], v[202:205], v[32:35]
	v_mfma_f32_16x16x32_bf16 v[20:23], v[174:177], v[210:213], v[20:23]
	v_mfma_f32_16x16x32_bf16 v[16:19], v[182:185], v[210:213], v[16:19]
	v_mfma_f32_16x16x32_bf16 v[4:7], v[174:177], v[218:221], v[4:7]
	v_mfma_f32_16x16x32_bf16 v[0:3], v[182:185], v[218:221], v[0:3]
	v_mfma_f32_16x16x32_bf16 v[52:55], v[178:181], v[194:197], v[52:55]
	v_mfma_f32_16x16x32_bf16 v[48:51], v[186:189], v[194:197], v[48:51]
	v_mfma_f32_16x16x32_bf16 v[36:39], v[178:181], v[206:209], v[36:39]
	v_mfma_f32_16x16x32_bf16 v[32:35], v[186:189], v[206:209], v[32:35]
	v_mfma_f32_16x16x32_bf16 v[20:23], v[178:181], v[214:217], v[20:23]
	v_mfma_f32_16x16x32_bf16 v[16:19], v[186:189], v[214:217], v[16:19]
	v_mfma_f32_16x16x32_bf16 v[4:7], v[178:181], v[222:225], v[4:7]
	v_mfma_f32_16x16x32_bf16 v[0:3], v[186:189], v[222:225], v[0:3]
	s_setprio 0
	s_barrier
	s_add_i32 vcc_hi, 0, 0x18000
	v_add_u32_e32 v136, vcc_hi, v156
	s_add_i32 s14, 0, 0x1c000
	ds_read_b128 v[152:155], v136
	ds_read_b128 v[162:165], v136 offset:1024
	ds_read_b128 v[166:169], v136 offset:2048
	ds_read_b128 v[170:173], v136 offset:3072
	v_add_u32_e32 v136, s14, v156
	ds_read_b128 v[174:177], v136
	ds_read_b128 v[178:181], v136 offset:1024
	ds_read_b128 v[182:185], v136 offset:2048
	ds_read_b128 v[186:189], v136 offset:3072
	s_add_u32 s12, s82, 0x40000
	s_addc_u32 s13, s83, 0
	s_mov_b32 m0, s77
	v_lshl_add_u64 v[234:235], s[12:13], 0, v[134:135]
	ds_read_b128 v[190:193], v161 offset:32768
	ds_read_b128 v[194:197], v161 offset:33792
	ds_read_b128 v[202:205], v161 offset:34816
	ds_read_b128 v[206:209], v161 offset:35840
	ds_read_b128 v[210:213], v161 offset:36864
	ds_read_b128 v[214:217], v161 offset:37888
	ds_read_b128 v[218:221], v161 offset:38912
	ds_read_b128 v[222:225], v161 offset:39936
	global_load_lds_dwordx4 v[234:235], off
	v_lshl_add_u64 v[234:235], s[12:13], 0, v[130:131]
	s_mov_b32 m0, s87
	s_nop 0
	global_load_lds_dwordx4 v[234:235], off
	s_waitcnt vmcnt(8)
	s_waitcnt lgkmcnt(0)
	s_barrier
	s_setprio 1
	s_waitcnt lgkmcnt(0)
	v_mfma_f32_16x16x32_bf16 v[124:127], v[152:155], v[190:193], v[124:127]
	v_mfma_f32_16x16x32_bf16 v[120:123], v[166:169], v[190:193], v[120:123]
	v_mfma_f32_16x16x32_bf16 v[108:111], v[152:155], v[202:205], v[108:111]
	v_mfma_f32_16x16x32_bf16 v[104:107], v[166:169], v[202:205], v[104:107]
	v_mfma_f32_16x16x32_bf16 v[92:95], v[152:155], v[210:213], v[92:95]
	v_mfma_f32_16x16x32_bf16 v[88:91], v[166:169], v[210:213], v[88:91]
	v_mfma_f32_16x16x32_bf16 v[76:79], v[152:155], v[218:221], v[76:79]
	v_mfma_f32_16x16x32_bf16 v[72:75], v[166:169], v[218:221], v[72:75]
	v_mfma_f32_16x16x32_bf16 v[124:127], v[162:165], v[194:197], v[124:127]
	v_mfma_f32_16x16x32_bf16 v[120:123], v[170:173], v[194:197], v[120:123]
	v_mfma_f32_16x16x32_bf16 v[108:111], v[162:165], v[206:209], v[108:111]
	v_mfma_f32_16x16x32_bf16 v[104:107], v[170:173], v[206:209], v[104:107]
	v_mfma_f32_16x16x32_bf16 v[92:95], v[162:165], v[214:217], v[92:95]
	v_mfma_f32_16x16x32_bf16 v[88:91], v[170:173], v[214:217], v[88:91]
	v_mfma_f32_16x16x32_bf16 v[76:79], v[162:165], v[222:225], v[76:79]
	v_mfma_f32_16x16x32_bf16 v[72:75], v[170:173], v[222:225], v[72:75]
	s_setprio 0
	s_setprio 1
	v_mfma_f32_16x16x32_bf16 v[116:119], v[174:177], v[190:193], v[116:119]
	v_mfma_f32_16x16x32_bf16 v[112:115], v[182:185], v[190:193], v[112:115]
	v_mfma_f32_16x16x32_bf16 v[100:103], v[174:177], v[202:205], v[100:103]
	v_mfma_f32_16x16x32_bf16 v[96:99], v[182:185], v[202:205], v[96:99]
	v_mfma_f32_16x16x32_bf16 v[84:87], v[174:177], v[210:213], v[84:87]
	v_mfma_f32_16x16x32_bf16 v[80:83], v[182:185], v[210:213], v[80:83]
	v_mfma_f32_16x16x32_bf16 v[68:71], v[174:177], v[218:221], v[68:71]
	v_mfma_f32_16x16x32_bf16 v[64:67], v[182:185], v[218:221], v[64:67]
	v_mfma_f32_16x16x32_bf16 v[116:119], v[178:181], v[194:197], v[116:119]
	v_mfma_f32_16x16x32_bf16 v[112:115], v[186:189], v[194:197], v[112:115]
	v_mfma_f32_16x16x32_bf16 v[100:103], v[178:181], v[206:209], v[100:103]
	v_mfma_f32_16x16x32_bf16 v[96:99], v[186:189], v[206:209], v[96:99]
	v_mfma_f32_16x16x32_bf16 v[84:87], v[178:181], v[214:217], v[84:87]
	v_mfma_f32_16x16x32_bf16 v[80:83], v[186:189], v[214:217], v[80:83]
	v_mfma_f32_16x16x32_bf16 v[68:71], v[178:181], v[222:225], v[68:71]
	v_mfma_f32_16x16x32_bf16 v[64:67], v[186:189], v[222:225], v[64:67]
	s_setprio 0
	s_barrier
	s_add_i32 s12, vcc_hi, s3
	v_lshl_add_u64 v[198:199], v[198:199], 0, s[90:91]
	s_mov_b32 m0, s12
	ds_read_b128 v[190:193], v161 offset:49152
	ds_read_b128 v[194:197], v161 offset:50176
	ds_read_b128 v[202:205], v161 offset:51200
	ds_read_b128 v[206:209], v161 offset:52224
	ds_read_b128 v[210:213], v161 offset:53248
	ds_read_b128 v[214:217], v161 offset:54272
	ds_read_b128 v[218:221], v161 offset:55296
	ds_read_b128 v[222:225], v161 offset:56320
	global_load_lds_dwordx4 v[198:199], off
	s_add_i32 m0, s12, 0x2000
	s_add_u32 s4, s4, 0x40080
	v_lshl_add_u64 v[198:199], v[226:227], 0, s[90:91]
	s_addc_u32 s5, s5, 0
	s_add_i32 s12, s14, s3
	global_load_lds_dwordx4 v[198:199], off
	v_lshl_add_u64 v[198:199], s[4:5], 0, v[132:133]
	s_mov_b32 m0, s12
	s_nop 0
	global_load_lds_dwordx4 v[198:199], off
	v_lshl_add_u64 v[198:199], s[4:5], 0, v[128:129]
	s_add_i32 m0, s12, 0x2000
	s_nop 0
	global_load_lds_dwordx4 v[198:199], off
	v_lshl_add_u64 v[198:199], v[228:229], 0, s[90:91]
	s_mov_b32 m0, s97
	s_nop 0
	global_load_lds_dwordx4 v[198:199], off
	v_lshl_add_u64 v[198:199], v[230:231], 0, s[90:91]
	s_mov_b32 m0, s99
	s_nop 0
	global_load_lds_dwordx4 v[198:199], off
	s_waitcnt vmcnt(8)
	s_waitcnt lgkmcnt(0)
	s_barrier
	s_setprio 1
	s_waitcnt lgkmcnt(0)
	v_mfma_f32_16x16x32_bf16 v[60:63], v[152:155], v[190:193], v[60:63]
	v_mfma_f32_16x16x32_bf16 v[56:59], v[166:169], v[190:193], v[56:59]
	v_mfma_f32_16x16x32_bf16 v[44:47], v[152:155], v[202:205], v[44:47]
	v_mfma_f32_16x16x32_bf16 v[40:43], v[166:169], v[202:205], v[40:43]
	v_mfma_f32_16x16x32_bf16 v[28:31], v[152:155], v[210:213], v[28:31]
	v_mfma_f32_16x16x32_bf16 v[24:27], v[166:169], v[210:213], v[24:27]
	v_mfma_f32_16x16x32_bf16 v[12:15], v[152:155], v[218:221], v[12:15]
	v_mfma_f32_16x16x32_bf16 v[8:11], v[166:169], v[218:221], v[8:11]
	v_mfma_f32_16x16x32_bf16 v[60:63], v[162:165], v[194:197], v[60:63]
	v_mfma_f32_16x16x32_bf16 v[56:59], v[170:173], v[194:197], v[56:59]
	v_mfma_f32_16x16x32_bf16 v[44:47], v[162:165], v[206:209], v[44:47]
	v_mfma_f32_16x16x32_bf16 v[40:43], v[170:173], v[206:209], v[40:43]
	v_mfma_f32_16x16x32_bf16 v[28:31], v[162:165], v[214:217], v[28:31]
	v_mfma_f32_16x16x32_bf16 v[24:27], v[170:173], v[214:217], v[24:27]
	v_mfma_f32_16x16x32_bf16 v[12:15], v[162:165], v[222:225], v[12:15]
	v_mfma_f32_16x16x32_bf16 v[8:11], v[170:173], v[222:225], v[8:11]
	s_setprio 0
	s_setprio 1
	v_mfma_f32_16x16x32_bf16 v[52:55], v[174:177], v[190:193], v[52:55]
	v_mfma_f32_16x16x32_bf16 v[48:51], v[182:185], v[190:193], v[48:51]
	v_mfma_f32_16x16x32_bf16 v[36:39], v[174:177], v[202:205], v[36:39]
	v_mfma_f32_16x16x32_bf16 v[32:35], v[182:185], v[202:205], v[32:35]
	v_mfma_f32_16x16x32_bf16 v[20:23], v[174:177], v[210:213], v[20:23]
	v_mfma_f32_16x16x32_bf16 v[16:19], v[182:185], v[210:213], v[16:19]
	v_mfma_f32_16x16x32_bf16 v[4:7], v[174:177], v[218:221], v[4:7]
	v_mfma_f32_16x16x32_bf16 v[0:3], v[182:185], v[218:221], v[0:3]
	v_mfma_f32_16x16x32_bf16 v[52:55], v[178:181], v[194:197], v[52:55]
	v_mfma_f32_16x16x32_bf16 v[48:51], v[186:189], v[194:197], v[48:51]
	v_mfma_f32_16x16x32_bf16 v[36:39], v[178:181], v[206:209], v[36:39]
	v_mfma_f32_16x16x32_bf16 v[32:35], v[186:189], v[206:209], v[32:35]
	v_mfma_f32_16x16x32_bf16 v[20:23], v[178:181], v[214:217], v[20:23]
	v_mfma_f32_16x16x32_bf16 v[16:19], v[186:189], v[214:217], v[16:19]
	v_mfma_f32_16x16x32_bf16 v[4:7], v[178:181], v[222:225], v[4:7]
	v_mfma_f32_16x16x32_bf16 v[0:3], v[186:189], v[222:225], v[0:3]
	s_setprio 0
	s_add_i32 vcc_lo, vcc_lo, 2
	s_add_u32 s0, s0, 0x100
	s_addc_u32 s1, s1, 0
	s_add_u32 s53, s53, 0x100
	s_addc_u32 s79, s79, 0
	s_cmp_gt_u32 vcc_lo, 13
	s_barrier
	s_cbranch_scc0 .LBB0_180
	s_and_b64 vcc, exec, s[92:93]
	s_cbranch_vccnz .LBB0_184
	s_cmp_gt_i32 s11, 3
	s_mov_b64 s[0:1], -1
	s_cbranch_scc1 .LBB0_185

.LBB0_306:
	ds_read_b128 v[112:115], v213
	ds_read_b128 v[116:119], v213 offset:1024
	ds_read_b128 v[136:139], v213 offset:2048
	ds_read_b128 v[140:143], v213 offset:3072
	ds_read_b128 v[144:147], v243
	ds_read_b128 v[148:151], v243 offset:1024
	ds_read_b128 v[152:155], v243 offset:2048
	ds_read_b128 v[156:159], v243 offset:3072
	s_add_u32 s17, s8, 0xfffc0080
	s_addc_u32 s26, s9, -1
	s_cmp_eq_u32 s16, 12
	s_cselect_b32 s73, s11, s26
	s_cselect_b32 s72, s87, s17
	s_cselect_b32 s41, s89, vcc_hi
	s_cselect_b32 s40, s95, vcc_lo
	v_lshl_add_u64 v[192:193], s[8:9], 0, v[220:221]
	s_add_i32 m0, s55, 0xc000
	ds_read_b128 v[160:163], v244
	ds_read_b128 v[164:167], v244 offset:1024
	ds_read_b128 v[168:171], v244 offset:2048
	ds_read_b128 v[172:175], v244 offset:3072
	ds_read_b128 v[176:179], v244 offset:4096
	ds_read_b128 v[180:183], v244 offset:5120
	ds_read_b128 v[184:187], v244 offset:6144
	ds_read_b128 v[188:191], v244 offset:7168
	global_load_lds_dwordx4 v[192:193], off
	v_lshl_add_u64 v[192:193], s[8:9], 0, v[222:223]
	s_add_i32 m0, s55, 0xe000
	s_nop 0
	global_load_lds_dwordx4 v[192:193], off
	s_waitcnt vmcnt(8)
	s_waitcnt lgkmcnt(0)
	s_barrier
	s_setprio 1
	s_waitcnt lgkmcnt(0)
	v_mfma_f32_16x16x32_bf16 v[132:135], v[112:115], v[160:163], v[132:135]
	v_mfma_f32_16x16x32_bf16 v[124:127], v[136:139], v[160:163], v[124:127]
	v_mfma_f32_16x16x32_bf16 v[108:111], v[112:115], v[168:171], v[108:111]
	v_mfma_f32_16x16x32_bf16 v[100:103], v[136:139], v[168:171], v[100:103]
	v_mfma_f32_16x16x32_bf16 v[92:95], v[112:115], v[176:179], v[92:95]
	v_mfma_f32_16x16x32_bf16 v[84:87], v[136:139], v[176:179], v[84:87]
	v_mfma_f32_16x16x32_bf16 v[76:79], v[112:115], v[184:187], v[76:79]
	v_mfma_f32_16x16x32_bf16 v[68:71], v[136:139], v[184:187], v[68:71]
	v_mfma_f32_16x16x32_bf16 v[132:135], v[116:119], v[164:167], v[132:135]
	v_mfma_f32_16x16x32_bf16 v[124:127], v[140:143], v[164:167], v[124:127]
	v_mfma_f32_16x16x32_bf16 v[108:111], v[116:119], v[172:175], v[108:111]
	v_mfma_f32_16x16x32_bf16 v[100:103], v[140:143], v[172:175], v[100:103]
	v_mfma_f32_16x16x32_bf16 v[92:95], v[116:119], v[180:183], v[92:95]
	v_mfma_f32_16x16x32_bf16 v[84:87], v[140:143], v[180:183], v[84:87]
	v_mfma_f32_16x16x32_bf16 v[76:79], v[116:119], v[188:191], v[76:79]
	v_mfma_f32_16x16x32_bf16 v[68:71], v[140:143], v[188:191], v[68:71]
	s_setprio 0
	s_setprio 1
	v_mfma_f32_16x16x32_bf16 v[128:131], v[144:147], v[160:163], v[128:131]
	v_mfma_f32_16x16x32_bf16 v[120:123], v[152:155], v[160:163], v[120:123]
	v_mfma_f32_16x16x32_bf16 v[104:107], v[144:147], v[168:171], v[104:107]
	v_mfma_f32_16x16x32_bf16 v[96:99], v[152:155], v[168:171], v[96:99]
	v_mfma_f32_16x16x32_bf16 v[88:91], v[144:147], v[176:179], v[88:91]
	v_mfma_f32_16x16x32_bf16 v[80:83], v[152:155], v[176:179], v[80:83]
	v_mfma_f32_16x16x32_bf16 v[72:75], v[144:147], v[184:187], v[72:75]
	v_mfma_f32_16x16x32_bf16 v[64:67], v[152:155], v[184:187], v[64:67]
	v_mfma_f32_16x16x32_bf16 v[128:131], v[148:151], v[164:167], v[128:131]
	v_mfma_f32_16x16x32_bf16 v[120:123], v[156:159], v[164:167], v[120:123]
	v_mfma_f32_16x16x32_bf16 v[104:107], v[148:151], v[172:175], v[104:107]
	v_mfma_f32_16x16x32_bf16 v[96:99], v[156:159], v[172:175], v[96:99]
	v_mfma_f32_16x16x32_bf16 v[88:91], v[148:151], v[180:183], v[88:91]
	v_mfma_f32_16x16x32_bf16 v[80:83], v[156:159], v[180:183], v[80:83]
	v_mfma_f32_16x16x32_bf16 v[72:75], v[148:151], v[188:191], v[72:75]
	v_mfma_f32_16x16x32_bf16 v[64:67], v[156:159], v[188:191], v[64:67]
	s_setprio 0
	s_barrier
	s_add_i32 s17, s3, s53
	v_lshl_add_u64 v[192:193], s[40:41], 0, v[204:205]
	s_mov_b32 m0, s17
	ds_read_b128 v[160:163], v244 offset:16384
	ds_read_b128 v[164:167], v244 offset:17408
	ds_read_b128 v[168:171], v244 offset:18432
	ds_read_b128 v[172:175], v244 offset:19456
	ds_read_b128 v[176:179], v244 offset:20480
	ds_read_b128 v[180:183], v244 offset:21504
	ds_read_b128 v[184:187], v244 offset:22528
	ds_read_b128 v[188:191], v244 offset:23552
	global_load_lds_dwordx4 v[192:193], off
	s_add_i32 m0, s17, 0x2000
	s_add_u32 s26, s40, 0x40000
	v_lshl_add_u64 v[194:195], s[40:41], 0, v[208:209]
	s_addc_u32 s27, s41, 0
	s_add_i32 s17, s33, s53
	global_load_lds_dwordx4 v[194:195], off
	v_lshl_add_u64 v[196:197], s[26:27], 0, v[204:205]
	s_mov_b32 m0, s17
	v_lshl_add_u64 v[198:199], s[72:73], 0, v[206:207]
	global_load_lds_dwordx4 v[196:197], off
	v_lshl_add_u64 v[196:197], s[26:27], 0, v[208:209]
	s_add_i32 m0, s17, 0x2000
	s_nop 0
	global_load_lds_dwordx4 v[196:197], off
	v_lshl_add_u64 v[196:197], s[72:73], 0, v[202:203]
	s_mov_b32 m0, s55
	s_nop 0
	global_load_lds_dwordx4 v[196:197], off
	s_mov_b32 m0, s63
	s_nop 0
	global_load_lds_dwordx4 v[198:199], off
	s_waitcnt vmcnt(8)
	s_waitcnt lgkmcnt(0)
	s_barrier
	s_setprio 1
	s_waitcnt lgkmcnt(0)
	v_mfma_f32_16x16x32_bf16 v[60:63], v[112:115], v[160:163], v[60:63]
	v_mfma_f32_16x16x32_bf16 v[52:55], v[136:139], v[160:163], v[52:55]
	v_mfma_f32_16x16x32_bf16 v[44:47], v[112:115], v[168:171], v[44:47]
	v_mfma_f32_16x16x32_bf16 v[36:39], v[136:139], v[168:171], v[36:39]
	v_mfma_f32_16x16x32_bf16 v[28:31], v[112:115], v[176:179], v[28:31]
	v_mfma_f32_16x16x32_bf16 v[20:23], v[136:139], v[176:179], v[20:23]
	v_mfma_f32_16x16x32_bf16 v[12:15], v[112:115], v[184:187], v[12:15]
	v_mfma_f32_16x16x32_bf16 v[4:7], v[136:139], v[184:187], v[4:7]
	v_mfma_f32_16x16x32_bf16 v[60:63], v[116:119], v[164:167], v[60:63]
	v_mfma_f32_16x16x32_bf16 v[52:55], v[140:143], v[164:167], v[52:55]
	v_mfma_f32_16x16x32_bf16 v[44:47], v[116:119], v[172:175], v[44:47]
	v_mfma_f32_16x16x32_bf16 v[36:39], v[140:143], v[172:175], v[36:39]
	v_mfma_f32_16x16x32_bf16 v[28:31], v[116:119], v[180:183], v[28:31]
	v_mfma_f32_16x16x32_bf16 v[20:23], v[140:143], v[180:183], v[20:23]
	v_mfma_f32_16x16x32_bf16 v[12:15], v[116:119], v[188:191], v[12:15]
	v_mfma_f32_16x16x32_bf16 v[4:7], v[140:143], v[188:191], v[4:7]
	s_setprio 0
	s_setprio 1
	v_mfma_f32_16x16x32_bf16 v[56:59], v[144:147], v[160:163], v[56:59]
	v_mfma_f32_16x16x32_bf16 v[48:51], v[152:155], v[160:163], v[48:51]
	v_mfma_f32_16x16x32_bf16 v[40:43], v[144:147], v[168:171], v[40:43]
	v_mfma_f32_16x16x32_bf16 v[32:35], v[152:155], v[168:171], v[32:35]
	v_mfma_f32_16x16x32_bf16 v[24:27], v[144:147], v[176:179], v[24:27]
	v_mfma_f32_16x16x32_bf16 v[16:19], v[152:155], v[176:179], v[16:19]
	v_mfma_f32_16x16x32_bf16 v[8:11], v[144:147], v[184:187], v[8:11]
	v_mfma_f32_16x16x32_bf16 v[0:3], v[152:155], v[184:187], v[0:3]
	v_mfma_f32_16x16x32_bf16 v[56:59], v[148:151], v[164:167], v[56:59]
	v_mfma_f32_16x16x32_bf16 v[48:51], v[156:159], v[164:167], v[48:51]
	v_mfma_f32_16x16x32_bf16 v[40:43], v[148:151], v[172:175], v[40:43]
	v_mfma_f32_16x16x32_bf16 v[32:35], v[156:159], v[172:175], v[32:35]
	v_mfma_f32_16x16x32_bf16 v[24:27], v[148:151], v[180:183], v[24:27]
	v_mfma_f32_16x16x32_bf16 v[16:19], v[156:159], v[180:183], v[16:19]
	v_mfma_f32_16x16x32_bf16 v[8:11], v[148:151], v[188:191], v[8:11]
	v_mfma_f32_16x16x32_bf16 v[0:3], v[156:159], v[188:191], v[0:3]
	s_setprio 0
	s_barrier
	s_add_i32 s17, 0, 0x18000
	s_add_i32 s28, 0, 0x1c000
	v_add_u32_e32 v140, s17, v235
	v_add_u32_e32 v156, s28, v235
	ds_read_b128 v[112:115], v140
	ds_read_b128 v[116:119], v140 offset:1024
	ds_read_b128 v[136:139], v140 offset:2048
	ds_read_b128 v[140:143], v140 offset:3072
	ds_read_b128 v[144:147], v156
	ds_read_b128 v[148:151], v156 offset:1024
	ds_read_b128 v[152:155], v156 offset:2048
	ds_read_b128 v[156:159], v156 offset:3072
	s_add_u32 s26, s72, 0x40000
	s_addc_u32 s27, s73, 0
	s_mov_b32 m0, s74
	v_lshl_add_u64 v[228:229], s[26:27], 0, v[202:203]
	ds_read_b128 v[160:163], v244 offset:32768
	ds_read_b128 v[164:167], v244 offset:33792
	ds_read_b128 v[168:171], v244 offset:34816
	ds_read_b128 v[172:175], v244 offset:35840
	ds_read_b128 v[176:179], v244 offset:36864
	ds_read_b128 v[180:183], v244 offset:37888
	ds_read_b128 v[184:187], v244 offset:38912
	ds_read_b128 v[188:191], v244 offset:39936
	global_load_lds_dwordx4 v[228:229], off
	v_lshl_add_u64 v[228:229], s[26:27], 0, v[206:207]
	s_mov_b32 m0, s76
	s_nop 0
	global_load_lds_dwordx4 v[228:229], off
	s_waitcnt vmcnt(8)
	s_waitcnt lgkmcnt(0)
	s_barrier
	s_setprio 1
	s_waitcnt lgkmcnt(0)
	v_mfma_f32_16x16x32_bf16 v[132:135], v[112:115], v[160:163], v[132:135]
	v_mfma_f32_16x16x32_bf16 v[124:127], v[136:139], v[160:163], v[124:127]
	v_mfma_f32_16x16x32_bf16 v[108:111], v[112:115], v[168:171], v[108:111]
	v_mfma_f32_16x16x32_bf16 v[100:103], v[136:139], v[168:171], v[100:103]
	v_mfma_f32_16x16x32_bf16 v[92:95], v[112:115], v[176:179], v[92:95]
	v_mfma_f32_16x16x32_bf16 v[84:87], v[136:139], v[176:179], v[84:87]
	v_mfma_f32_16x16x32_bf16 v[76:79], v[112:115], v[184:187], v[76:79]
	v_mfma_f32_16x16x32_bf16 v[68:71], v[136:139], v[184:187], v[68:71]
	v_mfma_f32_16x16x32_bf16 v[132:135], v[116:119], v[164:167], v[132:135]
	v_mfma_f32_16x16x32_bf16 v[124:127], v[140:143], v[164:167], v[124:127]
	v_mfma_f32_16x16x32_bf16 v[108:111], v[116:119], v[172:175], v[108:111]
	v_mfma_f32_16x16x32_bf16 v[100:103], v[140:143], v[172:175], v[100:103]
	v_mfma_f32_16x16x32_bf16 v[92:95], v[116:119], v[180:183], v[92:95]
	v_mfma_f32_16x16x32_bf16 v[84:87], v[140:143], v[180:183], v[84:87]
	v_mfma_f32_16x16x32_bf16 v[76:79], v[116:119], v[188:191], v[76:79]
	v_mfma_f32_16x16x32_bf16 v[68:71], v[140:143], v[188:191], v[68:71]
	s_setprio 0
	s_setprio 1
	v_mfma_f32_16x16x32_bf16 v[128:131], v[144:147], v[160:163], v[128:131]
	v_mfma_f32_16x16x32_bf16 v[120:123], v[152:155], v[160:163], v[120:123]
	v_mfma_f32_16x16x32_bf16 v[104:107], v[144:147], v[168:171], v[104:107]
	v_mfma_f32_16x16x32_bf16 v[96:99], v[152:155], v[168:171], v[96:99]
	v_mfma_f32_16x16x32_bf16 v[88:91], v[144:147], v[176:179], v[88:91]
	v_mfma_f32_16x16x32_bf16 v[80:83], v[152:155], v[176:179], v[80:83]
	v_mfma_f32_16x16x32_bf16 v[72:75], v[144:147], v[184:187], v[72:75]
	v_mfma_f32_16x16x32_bf16 v[64:67], v[152:155], v[184:187], v[64:67]
	v_mfma_f32_16x16x32_bf16 v[128:131], v[148:151], v[164:167], v[128:131]
	v_mfma_f32_16x16x32_bf16 v[120:123], v[156:159], v[164:167], v[120:123]
	v_mfma_f32_16x16x32_bf16 v[104:107], v[148:151], v[172:175], v[104:107]
	v_mfma_f32_16x16x32_bf16 v[96:99], v[156:159], v[172:175], v[96:99]
	v_mfma_f32_16x16x32_bf16 v[88:91], v[148:151], v[180:183], v[88:91]
	v_mfma_f32_16x16x32_bf16 v[80:83], v[156:159], v[180:183], v[80:83]
	v_mfma_f32_16x16x32_bf16 v[72:75], v[148:151], v[188:191], v[72:75]
	v_mfma_f32_16x16x32_bf16 v[64:67], v[156:159], v[188:191], v[64:67]
	s_setprio 0
	s_barrier
	s_add_i32 s17, s17, s53
	v_lshl_add_u64 v[192:193], v[192:193], 0, s[20:21]
	s_mov_b32 m0, s17
	ds_read_b128 v[160:163], v244 offset:49152
	ds_read_b128 v[164:167], v244 offset:50176
	ds_read_b128 v[168:171], v244 offset:51200
	ds_read_b128 v[172:175], v244 offset:52224
	ds_read_b128 v[176:179], v244 offset:53248
	ds_read_b128 v[180:183], v244 offset:54272
	ds_read_b128 v[184:187], v244 offset:55296
	ds_read_b128 v[188:191], v244 offset:56320
	global_load_lds_dwordx4 v[192:193], off
	s_add_i32 m0, s17, 0x2000
	s_add_u32 s26, s40, 0x40080
	v_lshl_add_u64 v[192:193], v[194:195], 0, s[20:21]
	s_addc_u32 s27, s41, 0
	s_add_i32 s17, s28, s53
	global_load_lds_dwordx4 v[192:193], off
	v_lshl_add_u64 v[192:193], s[26:27], 0, v[204:205]
	s_mov_b32 m0, s17
	s_nop 0
	global_load_lds_dwordx4 v[192:193], off
	v_lshl_add_u64 v[192:193], s[26:27], 0, v[208:209]
	s_add_i32 m0, s17, 0x2000
	s_nop 0
	global_load_lds_dwordx4 v[192:193], off
	v_lshl_add_u64 v[192:193], v[196:197], 0, s[20:21]
	s_mov_b32 m0, s78
	s_nop 0
	global_load_lds_dwordx4 v[192:193], off
	v_lshl_add_u64 v[192:193], v[198:199], 0, s[20:21]
	s_mov_b32 m0, s79
	s_nop 0
	global_load_lds_dwordx4 v[192:193], off
	s_waitcnt vmcnt(8)
	s_waitcnt lgkmcnt(0)
	s_barrier
	s_setprio 1
	s_waitcnt lgkmcnt(0)
	v_mfma_f32_16x16x32_bf16 v[60:63], v[112:115], v[160:163], v[60:63]
	v_mfma_f32_16x16x32_bf16 v[52:55], v[136:139], v[160:163], v[52:55]
	v_mfma_f32_16x16x32_bf16 v[44:47], v[112:115], v[168:171], v[44:47]
	v_mfma_f32_16x16x32_bf16 v[36:39], v[136:139], v[168:171], v[36:39]
	v_mfma_f32_16x16x32_bf16 v[28:31], v[112:115], v[176:179], v[28:31]
	v_mfma_f32_16x16x32_bf16 v[20:23], v[136:139], v[176:179], v[20:23]
	v_mfma_f32_16x16x32_bf16 v[12:15], v[112:115], v[184:187], v[12:15]
	v_mfma_f32_16x16x32_bf16 v[4:7], v[136:139], v[184:187], v[4:7]
	v_mfma_f32_16x16x32_bf16 v[60:63], v[116:119], v[164:167], v[60:63]
	v_mfma_f32_16x16x32_bf16 v[52:55], v[140:143], v[164:167], v[52:55]
	v_mfma_f32_16x16x32_bf16 v[44:47], v[116:119], v[172:175], v[44:47]
	v_mfma_f32_16x16x32_bf16 v[36:39], v[140:143], v[172:175], v[36:39]
	v_mfma_f32_16x16x32_bf16 v[28:31], v[116:119], v[180:183], v[28:31]
	v_mfma_f32_16x16x32_bf16 v[20:23], v[140:143], v[180:183], v[20:23]
	v_mfma_f32_16x16x32_bf16 v[12:15], v[116:119], v[188:191], v[12:15]
	v_mfma_f32_16x16x32_bf16 v[4:7], v[140:143], v[188:191], v[4:7]
	s_setprio 0
	s_setprio 1
	v_mfma_f32_16x16x32_bf16 v[56:59], v[144:147], v[160:163], v[56:59]
	v_mfma_f32_16x16x32_bf16 v[48:51], v[152:155], v[160:163], v[48:51]
	v_mfma_f32_16x16x32_bf16 v[40:43], v[144:147], v[168:171], v[40:43]
	v_mfma_f32_16x16x32_bf16 v[32:35], v[152:155], v[168:171], v[32:35]
	v_mfma_f32_16x16x32_bf16 v[24:27], v[144:147], v[176:179], v[24:27]
	v_mfma_f32_16x16x32_bf16 v[16:19], v[152:155], v[176:179], v[16:19]
	v_mfma_f32_16x16x32_bf16 v[8:11], v[144:147], v[184:187], v[8:11]
	v_mfma_f32_16x16x32_bf16 v[0:3], v[152:155], v[184:187], v[0:3]
	v_mfma_f32_16x16x32_bf16 v[56:59], v[148:151], v[164:167], v[56:59]
	v_mfma_f32_16x16x32_bf16 v[48:51], v[156:159], v[164:167], v[48:51]
	v_mfma_f32_16x16x32_bf16 v[40:43], v[148:151], v[172:175], v[40:43]
	v_mfma_f32_16x16x32_bf16 v[32:35], v[156:159], v[172:175], v[32:35]
	v_mfma_f32_16x16x32_bf16 v[24:27], v[148:151], v[180:183], v[24:27]
	v_mfma_f32_16x16x32_bf16 v[16:19], v[156:159], v[180:183], v[16:19]
	v_mfma_f32_16x16x32_bf16 v[8:11], v[148:151], v[188:191], v[8:11]
	v_mfma_f32_16x16x32_bf16 v[0:3], v[156:159], v[188:191], v[0:3]
	s_setprio 0
	s_add_i32 s16, s16, 2
	s_add_u32 s8, s8, 0x100
	s_addc_u32 s9, s9, 0
	s_add_u32 vcc_lo, vcc_lo, 0x100
	s_addc_u32 vcc_hi, vcc_hi, 0
	s_cmp_gt_u32 s16, 13
	s_barrier
	s_cbranch_scc0 .LBB0_306
	s_and_b64 vcc, exec, s[22:23]
	s_cbranch_vccnz .LBB0_311
	s_lshl_b32 s87, s10, 7
	s_cmp_gt_i32 s10, 7
	s_mov_b64 s[8:9], -1
	s_cbranch_scc1 .LBB0_312

.LBB0_495:
	v_add_u32_e32 v147, s53, v145
	ds_read_b128 v[148:151], v147
	ds_read_b128 v[152:155], v147 offset:1024
	ds_read_b128 v[156:159], v147 offset:2048
	ds_read_b128 v[160:163], v147 offset:3072
	v_add_u32_e32 v147, s54, v145
	s_add_u32 s34, s16, s30
	ds_read_b128 v[164:167], v147
	ds_read_b128 v[172:175], v147 offset:1024
	ds_read_b128 v[176:179], v147 offset:2048
	ds_read_b128 v[180:183], v147 offset:3072
	s_addc_u32 s35, s17, s31
	s_add_u32 s34, s34, 0x100
	s_addc_u32 s35, s35, 0
	s_add_u32 s59, s27, s30
	s_addc_u32 s60, s55, s31
	s_cmpk_eq_i32 s30, 0xf00
	s_cselect_b32 s37, s21, s35
	s_cselect_b32 s36, s23, s34
	s_cselect_b32 s35, s56, s60
	s_cselect_b32 s34, s57, s59
	v_lshl_add_u64 v[168:169], v[140:141], 0, s[30:31]
	s_add_i32 m0, s40, 0xc000
	ds_read_b128 v[184:187], v146
	ds_read_b128 v[188:191], v146 offset:1024
	ds_read_b128 v[192:195], v146 offset:2048
	ds_read_b128 v[196:199], v146 offset:3072
	ds_read_b128 v[202:205], v146 offset:4096
	ds_read_b128 v[206:209], v146 offset:5120
	ds_read_b128 v[210:213], v146 offset:6144
	ds_read_b128 v[214:217], v146 offset:7168
	global_load_lds_dwordx4 v[168:169], off
	v_lshl_add_u64 v[168:169], v[142:143], 0, s[30:31]
	s_add_i32 m0, s40, 0xe000
	s_nop 0
	global_load_lds_dwordx4 v[168:169], off
	s_waitcnt vmcnt(8)
	s_waitcnt lgkmcnt(0)
	s_barrier
	s_setprio 1
	s_waitcnt lgkmcnt(0)
	v_mfma_f32_16x16x32_bf16 v[124:127], v[148:151], v[184:187], v[124:127]
	v_mfma_f32_16x16x32_bf16 v[120:123], v[156:159], v[184:187], v[120:123]
	v_mfma_f32_16x16x32_bf16 v[108:111], v[148:151], v[192:195], v[108:111]
	v_mfma_f32_16x16x32_bf16 v[104:107], v[156:159], v[192:195], v[104:107]
	v_mfma_f32_16x16x32_bf16 v[92:95], v[148:151], v[202:205], v[92:95]
	v_mfma_f32_16x16x32_bf16 v[88:91], v[156:159], v[202:205], v[88:91]
	v_mfma_f32_16x16x32_bf16 v[76:79], v[148:151], v[210:213], v[76:79]
	v_mfma_f32_16x16x32_bf16 v[72:75], v[156:159], v[210:213], v[72:75]
	v_mfma_f32_16x16x32_bf16 v[124:127], v[152:155], v[188:191], v[124:127]
	v_mfma_f32_16x16x32_bf16 v[120:123], v[160:163], v[188:191], v[120:123]
	v_mfma_f32_16x16x32_bf16 v[108:111], v[152:155], v[196:199], v[108:111]
	v_mfma_f32_16x16x32_bf16 v[104:107], v[160:163], v[196:199], v[104:107]
	v_mfma_f32_16x16x32_bf16 v[92:95], v[152:155], v[206:209], v[92:95]
	v_mfma_f32_16x16x32_bf16 v[88:91], v[160:163], v[206:209], v[88:91]
	v_mfma_f32_16x16x32_bf16 v[76:79], v[152:155], v[214:217], v[76:79]
	v_mfma_f32_16x16x32_bf16 v[72:75], v[160:163], v[214:217], v[72:75]
	s_setprio 0
	s_setprio 1
	v_mfma_f32_16x16x32_bf16 v[116:119], v[164:167], v[184:187], v[116:119]
	v_mfma_f32_16x16x32_bf16 v[112:115], v[176:179], v[184:187], v[112:115]
	v_mfma_f32_16x16x32_bf16 v[100:103], v[164:167], v[192:195], v[100:103]
	v_mfma_f32_16x16x32_bf16 v[96:99], v[176:179], v[192:195], v[96:99]
	v_mfma_f32_16x16x32_bf16 v[84:87], v[164:167], v[202:205], v[84:87]
	v_mfma_f32_16x16x32_bf16 v[80:83], v[176:179], v[202:205], v[80:83]
	v_mfma_f32_16x16x32_bf16 v[68:71], v[164:167], v[210:213], v[68:71]
	v_mfma_f32_16x16x32_bf16 v[64:67], v[176:179], v[210:213], v[64:67]
	v_mfma_f32_16x16x32_bf16 v[116:119], v[172:175], v[188:191], v[116:119]
	v_mfma_f32_16x16x32_bf16 v[112:115], v[180:183], v[188:191], v[112:115]
	v_mfma_f32_16x16x32_bf16 v[100:103], v[172:175], v[196:199], v[100:103]
	v_mfma_f32_16x16x32_bf16 v[96:99], v[180:183], v[196:199], v[96:99]
	v_mfma_f32_16x16x32_bf16 v[84:87], v[172:175], v[206:209], v[84:87]
	v_mfma_f32_16x16x32_bf16 v[80:83], v[180:183], v[206:209], v[80:83]
	v_mfma_f32_16x16x32_bf16 v[68:71], v[172:175], v[214:217], v[68:71]
	v_mfma_f32_16x16x32_bf16 v[64:67], v[180:183], v[214:217], v[64:67]
	s_setprio 0
	s_barrier
	s_add_i32 s59, s53, s39
	v_lshl_add_u64 v[168:169], s[34:35], 0, v[128:129]
	s_mov_b32 m0, s59
	ds_read_b128 v[184:187], v146 offset:16384
	ds_read_b128 v[188:191], v146 offset:17408
	ds_read_b128 v[192:195], v146 offset:18432
	ds_read_b128 v[196:199], v146 offset:19456
	ds_read_b128 v[202:205], v146 offset:20480
	ds_read_b128 v[206:209], v146 offset:21504
	ds_read_b128 v[210:213], v146 offset:22528
	ds_read_b128 v[214:217], v146 offset:23552
	global_load_lds_dwordx4 v[168:169], off
	s_add_i32 m0, s59, 0x2000
	s_add_u32 s60, s34, 0x80000
	v_lshl_add_u64 v[218:219], s[34:35], 0, v[130:131]
	s_addc_u32 s61, s35, 0
	s_add_i32 s59, s54, s39
	global_load_lds_dwordx4 v[218:219], off
	v_lshl_add_u64 v[220:221], s[60:61], 0, v[128:129]
	s_mov_b32 m0, s59
	v_lshl_add_u64 v[222:223], s[36:37], 0, v[130:131]
	global_load_lds_dwordx4 v[220:221], off
	v_lshl_add_u64 v[220:221], s[60:61], 0, v[130:131]
	s_add_i32 m0, s59, 0x2000
	s_nop 0
	global_load_lds_dwordx4 v[220:221], off
	v_lshl_add_u64 v[220:221], s[36:37], 0, v[128:129]
	s_mov_b32 m0, s40
	s_nop 0
	global_load_lds_dwordx4 v[220:221], off
	s_mov_b32 m0, s41
	s_nop 0
	global_load_lds_dwordx4 v[222:223], off
	s_waitcnt vmcnt(8)
	s_waitcnt lgkmcnt(0)
	s_barrier
	s_setprio 1
	s_waitcnt lgkmcnt(0)
	v_mfma_f32_16x16x32_bf16 v[60:63], v[148:151], v[184:187], v[60:63]
	v_mfma_f32_16x16x32_bf16 v[56:59], v[156:159], v[184:187], v[56:59]
	v_mfma_f32_16x16x32_bf16 v[44:47], v[148:151], v[192:195], v[44:47]
	v_mfma_f32_16x16x32_bf16 v[40:43], v[156:159], v[192:195], v[40:43]
	v_mfma_f32_16x16x32_bf16 v[28:31], v[148:151], v[202:205], v[28:31]
	v_mfma_f32_16x16x32_bf16 v[24:27], v[156:159], v[202:205], v[24:27]
	v_mfma_f32_16x16x32_bf16 v[12:15], v[148:151], v[210:213], v[12:15]
	v_mfma_f32_16x16x32_bf16 v[8:11], v[156:159], v[210:213], v[8:11]
	v_mfma_f32_16x16x32_bf16 v[60:63], v[152:155], v[188:191], v[60:63]
	v_mfma_f32_16x16x32_bf16 v[56:59], v[160:163], v[188:191], v[56:59]
	v_mfma_f32_16x16x32_bf16 v[44:47], v[152:155], v[196:199], v[44:47]
	v_mfma_f32_16x16x32_bf16 v[40:43], v[160:163], v[196:199], v[40:43]
	v_mfma_f32_16x16x32_bf16 v[28:31], v[152:155], v[206:209], v[28:31]
	v_mfma_f32_16x16x32_bf16 v[24:27], v[160:163], v[206:209], v[24:27]
	v_mfma_f32_16x16x32_bf16 v[12:15], v[152:155], v[214:217], v[12:15]
	v_mfma_f32_16x16x32_bf16 v[8:11], v[160:163], v[214:217], v[8:11]
	s_setprio 0
	s_setprio 1
	v_mfma_f32_16x16x32_bf16 v[52:55], v[164:167], v[184:187], v[52:55]
	v_mfma_f32_16x16x32_bf16 v[48:51], v[176:179], v[184:187], v[48:51]
	v_mfma_f32_16x16x32_bf16 v[36:39], v[164:167], v[192:195], v[36:39]
	v_mfma_f32_16x16x32_bf16 v[32:35], v[176:179], v[192:195], v[32:35]
	v_mfma_f32_16x16x32_bf16 v[20:23], v[164:167], v[202:205], v[20:23]
	v_mfma_f32_16x16x32_bf16 v[16:19], v[176:179], v[202:205], v[16:19]
	v_mfma_f32_16x16x32_bf16 v[4:7], v[164:167], v[210:213], v[4:7]
	v_mfma_f32_16x16x32_bf16 v[0:3], v[176:179], v[210:213], v[0:3]
	v_mfma_f32_16x16x32_bf16 v[52:55], v[172:175], v[188:191], v[52:55]
	v_mfma_f32_16x16x32_bf16 v[48:51], v[180:183], v[188:191], v[48:51]
	v_mfma_f32_16x16x32_bf16 v[36:39], v[172:175], v[196:199], v[36:39]
	v_mfma_f32_16x16x32_bf16 v[32:35], v[180:183], v[196:199], v[32:35]
	v_mfma_f32_16x16x32_bf16 v[20:23], v[172:175], v[206:209], v[20:23]
	v_mfma_f32_16x16x32_bf16 v[16:19], v[180:183], v[206:209], v[16:19]
	v_mfma_f32_16x16x32_bf16 v[4:7], v[172:175], v[214:217], v[4:7]
	v_mfma_f32_16x16x32_bf16 v[0:3], v[180:183], v[214:217], v[0:3]
	s_setprio 0
	s_barrier
	s_add_i32 s59, 0, 0x18000
	v_add_u32_e32 v147, s59, v145
	s_add_i32 s60, 0, 0x1c000
	ds_read_b128 v[148:151], v147
	ds_read_b128 v[152:155], v147 offset:1024
	ds_read_b128 v[156:159], v147 offset:2048
	ds_read_b128 v[160:163], v147 offset:3072
	v_add_u32_e32 v147, s60, v145
	ds_read_b128 v[164:167], v147
	ds_read_b128 v[172:175], v147 offset:1024
	ds_read_b128 v[176:179], v147 offset:2048
	ds_read_b128 v[180:183], v147 offset:3072
	s_add_u32 s36, s36, 0x80000
	s_addc_u32 s37, s37, 0
	s_mov_b32 m0, s43
	v_lshl_add_u64 v[224:225], s[36:37], 0, v[128:129]
	ds_read_b128 v[184:187], v146 offset:32768
	ds_read_b128 v[188:191], v146 offset:33792
	ds_read_b128 v[192:195], v146 offset:34816
	ds_read_b128 v[196:199], v146 offset:35840
	ds_read_b128 v[202:205], v146 offset:36864
	ds_read_b128 v[206:209], v146 offset:37888
	ds_read_b128 v[210:213], v146 offset:38912
	ds_read_b128 v[214:217], v146 offset:39936
	global_load_lds_dwordx4 v[224:225], off
	v_lshl_add_u64 v[224:225], s[36:37], 0, v[130:131]
	s_mov_b32 m0, s48
	s_nop 0
	global_load_lds_dwordx4 v[224:225], off
	s_waitcnt vmcnt(8)
	s_waitcnt lgkmcnt(0)
	s_barrier
	s_setprio 1
	s_waitcnt lgkmcnt(0)
	v_mfma_f32_16x16x32_bf16 v[124:127], v[148:151], v[184:187], v[124:127]
	v_mfma_f32_16x16x32_bf16 v[120:123], v[156:159], v[184:187], v[120:123]
	v_mfma_f32_16x16x32_bf16 v[108:111], v[148:151], v[192:195], v[108:111]
	v_mfma_f32_16x16x32_bf16 v[104:107], v[156:159], v[192:195], v[104:107]
	v_mfma_f32_16x16x32_bf16 v[92:95], v[148:151], v[202:205], v[92:95]
	v_mfma_f32_16x16x32_bf16 v[88:91], v[156:159], v[202:205], v[88:91]
	v_mfma_f32_16x16x32_bf16 v[76:79], v[148:151], v[210:213], v[76:79]
	v_mfma_f32_16x16x32_bf16 v[72:75], v[156:159], v[210:213], v[72:75]
	v_mfma_f32_16x16x32_bf16 v[124:127], v[152:155], v[188:191], v[124:127]
	v_mfma_f32_16x16x32_bf16 v[120:123], v[160:163], v[188:191], v[120:123]
	v_mfma_f32_16x16x32_bf16 v[108:111], v[152:155], v[196:199], v[108:111]
	v_mfma_f32_16x16x32_bf16 v[104:107], v[160:163], v[196:199], v[104:107]
	v_mfma_f32_16x16x32_bf16 v[92:95], v[152:155], v[206:209], v[92:95]
	v_mfma_f32_16x16x32_bf16 v[88:91], v[160:163], v[206:209], v[88:91]
	v_mfma_f32_16x16x32_bf16 v[76:79], v[152:155], v[214:217], v[76:79]
	v_mfma_f32_16x16x32_bf16 v[72:75], v[160:163], v[214:217], v[72:75]
	s_setprio 0
	s_setprio 1
	v_mfma_f32_16x16x32_bf16 v[116:119], v[164:167], v[184:187], v[116:119]
	v_mfma_f32_16x16x32_bf16 v[112:115], v[176:179], v[184:187], v[112:115]
	v_mfma_f32_16x16x32_bf16 v[100:103], v[164:167], v[192:195], v[100:103]
	v_mfma_f32_16x16x32_bf16 v[96:99], v[176:179], v[192:195], v[96:99]
	v_mfma_f32_16x16x32_bf16 v[84:87], v[164:167], v[202:205], v[84:87]
	v_mfma_f32_16x16x32_bf16 v[80:83], v[176:179], v[202:205], v[80:83]
	v_mfma_f32_16x16x32_bf16 v[68:71], v[164:167], v[210:213], v[68:71]
	v_mfma_f32_16x16x32_bf16 v[64:67], v[176:179], v[210:213], v[64:67]
	v_mfma_f32_16x16x32_bf16 v[116:119], v[172:175], v[188:191], v[116:119]
	v_mfma_f32_16x16x32_bf16 v[112:115], v[180:183], v[188:191], v[112:115]
	v_mfma_f32_16x16x32_bf16 v[100:103], v[172:175], v[196:199], v[100:103]
	v_mfma_f32_16x16x32_bf16 v[96:99], v[180:183], v[196:199], v[96:99]
	v_mfma_f32_16x16x32_bf16 v[84:87], v[172:175], v[206:209], v[84:87]
	v_mfma_f32_16x16x32_bf16 v[80:83], v[180:183], v[206:209], v[80:83]
	v_mfma_f32_16x16x32_bf16 v[68:71], v[172:175], v[214:217], v[68:71]
	v_mfma_f32_16x16x32_bf16 v[64:67], v[180:183], v[214:217], v[64:67]
	s_setprio 0
	s_barrier
	s_add_i32 s36, s59, s39
	v_lshl_add_u64 v[168:169], v[168:169], 0, s[18:19]
	s_mov_b32 m0, s36
	ds_read_b128 v[184:187], v146 offset:49152
	ds_read_b128 v[188:191], v146 offset:50176
	ds_read_b128 v[192:195], v146 offset:51200
	ds_read_b128 v[196:199], v146 offset:52224
	ds_read_b128 v[202:205], v146 offset:53248
	ds_read_b128 v[206:209], v146 offset:54272
	ds_read_b128 v[210:213], v146 offset:55296
	ds_read_b128 v[214:217], v146 offset:56320
	global_load_lds_dwordx4 v[168:169], off
	s_add_i32 m0, s36, 0x2000
	s_add_u32 s34, s34, 0x80080
	v_lshl_add_u64 v[168:169], v[218:219], 0, s[18:19]
	s_addc_u32 s35, s35, 0
	s_add_i32 s36, s60, s39
	global_load_lds_dwordx4 v[168:169], off
	v_lshl_add_u64 v[168:169], s[34:35], 0, v[128:129]
	s_mov_b32 m0, s36
	s_nop 0
	global_load_lds_dwordx4 v[168:169], off
	v_lshl_add_u64 v[168:169], s[34:35], 0, v[130:131]
	s_add_i32 m0, s36, 0x2000
	s_nop 0
	global_load_lds_dwordx4 v[168:169], off
	v_lshl_add_u64 v[168:169], v[220:221], 0, s[18:19]
	s_mov_b32 m0, s49
	s_nop 0
	global_load_lds_dwordx4 v[168:169], off
	v_lshl_add_u64 v[168:169], v[222:223], 0, s[18:19]
	s_mov_b32 m0, s50
	s_nop 0
	global_load_lds_dwordx4 v[168:169], off
	s_waitcnt vmcnt(8)
	s_waitcnt lgkmcnt(0)
	s_barrier
	s_setprio 1
	s_waitcnt lgkmcnt(0)
	v_mfma_f32_16x16x32_bf16 v[60:63], v[148:151], v[184:187], v[60:63]
	v_mfma_f32_16x16x32_bf16 v[56:59], v[156:159], v[184:187], v[56:59]
	v_mfma_f32_16x16x32_bf16 v[44:47], v[148:151], v[192:195], v[44:47]
	v_mfma_f32_16x16x32_bf16 v[40:43], v[156:159], v[192:195], v[40:43]
	v_mfma_f32_16x16x32_bf16 v[28:31], v[148:151], v[202:205], v[28:31]
	v_mfma_f32_16x16x32_bf16 v[24:27], v[156:159], v[202:205], v[24:27]
	v_mfma_f32_16x16x32_bf16 v[12:15], v[148:151], v[210:213], v[12:15]
	v_mfma_f32_16x16x32_bf16 v[8:11], v[156:159], v[210:213], v[8:11]
	v_mfma_f32_16x16x32_bf16 v[60:63], v[152:155], v[188:191], v[60:63]
	v_mfma_f32_16x16x32_bf16 v[56:59], v[160:163], v[188:191], v[56:59]
	v_mfma_f32_16x16x32_bf16 v[44:47], v[152:155], v[196:199], v[44:47]
	v_mfma_f32_16x16x32_bf16 v[40:43], v[160:163], v[196:199], v[40:43]
	v_mfma_f32_16x16x32_bf16 v[28:31], v[152:155], v[206:209], v[28:31]
	v_mfma_f32_16x16x32_bf16 v[24:27], v[160:163], v[206:209], v[24:27]
	v_mfma_f32_16x16x32_bf16 v[12:15], v[152:155], v[214:217], v[12:15]
	v_mfma_f32_16x16x32_bf16 v[8:11], v[160:163], v[214:217], v[8:11]
	s_setprio 0
	s_setprio 1
	v_mfma_f32_16x16x32_bf16 v[52:55], v[164:167], v[184:187], v[52:55]
	v_mfma_f32_16x16x32_bf16 v[48:51], v[176:179], v[184:187], v[48:51]
	v_mfma_f32_16x16x32_bf16 v[36:39], v[164:167], v[192:195], v[36:39]
	v_mfma_f32_16x16x32_bf16 v[32:35], v[176:179], v[192:195], v[32:35]
	v_mfma_f32_16x16x32_bf16 v[20:23], v[164:167], v[202:205], v[20:23]
	v_mfma_f32_16x16x32_bf16 v[16:19], v[176:179], v[202:205], v[16:19]
	v_mfma_f32_16x16x32_bf16 v[4:7], v[164:167], v[210:213], v[4:7]
	v_mfma_f32_16x16x32_bf16 v[0:3], v[176:179], v[210:213], v[0:3]
	v_mfma_f32_16x16x32_bf16 v[52:55], v[172:175], v[188:191], v[52:55]
	v_mfma_f32_16x16x32_bf16 v[48:51], v[180:183], v[188:191], v[48:51]
	v_mfma_f32_16x16x32_bf16 v[36:39], v[172:175], v[196:199], v[36:39]
	v_mfma_f32_16x16x32_bf16 v[32:35], v[180:183], v[196:199], v[32:35]
	v_mfma_f32_16x16x32_bf16 v[20:23], v[172:175], v[206:209], v[20:23]
	v_mfma_f32_16x16x32_bf16 v[16:19], v[180:183], v[206:209], v[16:19]
	v_mfma_f32_16x16x32_bf16 v[4:7], v[172:175], v[214:217], v[4:7]
	v_mfma_f32_16x16x32_bf16 v[0:3], v[180:183], v[214:217], v[0:3]
	s_setprio 0
	s_add_i32 s58, s58, 2
	s_add_u32 s30, s30, 0x100
	s_addc_u32 s31, s31, 0
	s_cmp_gt_u32 s58, 29
	s_barrier
	s_cbranch_scc0 .LBB0_495
	s_add_u32 s30, s27, 0xffffff00
	s_addc_u32 s31, s55, -1
	s_andn2_b64 vcc, exec, s[4:5]
	s_cbranch_vccnz .LBB0_498
	v_mov_b32_e32 v0, 0
	s_mov_b32 s51, s20
	s_mov_b32 s14, s22
	s_mov_b64 s[16:17], s[28:29]
	s_mov_b32 s52, s26
	v_mov_b32_e32 v1, v0
	v_mov_b32_e32 v2, v0
	v_mov_b32_e32 v3, v0
	v_mov_b32_e32 v4, v0
	v_mov_b32_e32 v5, v0
	v_mov_b32_e32 v6, v0
	v_mov_b32_e32 v7, v0
	v_mov_b32_e32 v16, v0
	v_mov_b32_e32 v17, v0
	v_mov_b32_e32 v18, v0
	v_mov_b32_e32 v19, v0
	v_mov_b32_e32 v20, v0
	v_mov_b32_e32 v21, v0
	v_mov_b32_e32 v22, v0
	v_mov_b32_e32 v23, v0
	v_mov_b32_e32 v32, v0
	v_mov_b32_e32 v33, v0
	v_mov_b32_e32 v34, v0
	v_mov_b32_e32 v35, v0
	v_mov_b32_e32 v36, v0
	v_mov_b32_e32 v37, v0
	v_mov_b32_e32 v38, v0
	v_mov_b32_e32 v39, v0
	v_mov_b32_e32 v48, v0
	v_mov_b32_e32 v49, v0
	v_mov_b32_e32 v50, v0
	v_mov_b32_e32 v51, v0
	v_mov_b32_e32 v52, v0
	v_mov_b32_e32 v53, v0
	v_mov_b32_e32 v54, v0
	v_mov_b32_e32 v55, v0
	v_mov_b32_e32 v8, v0
	v_mov_b32_e32 v9, v0
	v_mov_b32_e32 v10, v0
	v_mov_b32_e32 v11, v0
	v_mov_b32_e32 v12, v0
	v_mov_b32_e32 v13, v0
	v_mov_b32_e32 v14, v0
	v_mov_b32_e32 v15, v0
	v_mov_b32_e32 v24, v0
	v_mov_b32_e32 v25, v0
	v_mov_b32_e32 v26, v0
	v_mov_b32_e32 v27, v0
	v_mov_b32_e32 v28, v0
	v_mov_b32_e32 v29, v0
	v_mov_b32_e32 v30, v0
	v_mov_b32_e32 v31, v0
	v_mov_b32_e32 v40, v0
	v_mov_b32_e32 v41, v0
	v_mov_b32_e32 v42, v0
	v_mov_b32_e32 v43, v0
	v_mov_b32_e32 v44, v0
	v_mov_b32_e32 v45, v0
	v_mov_b32_e32 v46, v0
	v_mov_b32_e32 v47, v0
	v_mov_b32_e32 v56, v0
	v_mov_b32_e32 v57, v0
	v_mov_b32_e32 v58, v0
	v_mov_b32_e32 v59, v0
	v_mov_b32_e32 v60, v0
	v_mov_b32_e32 v61, v0
	v_mov_b32_e32 v62, v0
	v_mov_b32_e32 v63, v0
	v_mov_b32_e32 v64, v0
	v_mov_b32_e32 v65, v0
	v_mov_b32_e32 v66, v0
	v_mov_b32_e32 v67, v0
	v_mov_b32_e32 v68, v0
	v_mov_b32_e32 v69, v0
	v_mov_b32_e32 v70, v0
	v_mov_b32_e32 v71, v0
	v_mov_b32_e32 v80, v0
	v_mov_b32_e32 v81, v0
	v_mov_b32_e32 v82, v0
	v_mov_b32_e32 v83, v0
	v_mov_b32_e32 v84, v0
	v_mov_b32_e32 v85, v0
	v_mov_b32_e32 v86, v0
	v_mov_b32_e32 v87, v0
	v_mov_b32_e32 v96, v0
	v_mov_b32_e32 v97, v0
	v_mov_b32_e32 v98, v0
	v_mov_b32_e32 v99, v0
	v_mov_b32_e32 v100, v0
	v_mov_b32_e32 v101, v0
	v_mov_b32_e32 v102, v0
	v_mov_b32_e32 v103, v0
	v_mov_b32_e32 v112, v0
	v_mov_b32_e32 v113, v0
	v_mov_b32_e32 v114, v0
	v_mov_b32_e32 v115, v0
	v_mov_b32_e32 v116, v0
	v_mov_b32_e32 v117, v0
	v_mov_b32_e32 v118, v0
	v_mov_b32_e32 v119, v0
	v_mov_b32_e32 v72, v0
	v_mov_b32_e32 v73, v0
	v_mov_b32_e32 v74, v0
	v_mov_b32_e32 v75, v0
	v_mov_b32_e32 v76, v0
	v_mov_b32_e32 v77, v0
	v_mov_b32_e32 v78, v0
	v_mov_b32_e32 v79, v0
	v_mov_b32_e32 v88, v0
	v_mov_b32_e32 v89, v0
	v_mov_b32_e32 v90, v0
	v_mov_b32_e32 v91, v0
	v_mov_b32_e32 v92, v0
	v_mov_b32_e32 v93, v0
	v_mov_b32_e32 v94, v0
	v_mov_b32_e32 v95, v0
	v_mov_b32_e32 v104, v0
	v_mov_b32_e32 v105, v0
	v_mov_b32_e32 v106, v0
	v_mov_b32_e32 v107, v0
	v_mov_b32_e32 v108, v0
	v_mov_b32_e32 v109, v0
	v_mov_b32_e32 v110, v0
	v_mov_b32_e32 v111, v0
	v_mov_b32_e32 v120, v0
	v_mov_b32_e32 v121, v0
	v_mov_b32_e32 v122, v0
	v_mov_b32_e32 v123, v0
	v_mov_b32_e32 v124, v0
	v_mov_b32_e32 v125, v0
	v_mov_b32_e32 v126, v0
	v_mov_b32_e32 v127, v0
	s_andn2_b64 vcc, exec, s[0:1]
	s_cbranch_vccnz .LBB0_499
	s_branch .LBB0_500
